# MLA attention phase: one static s_setprio 1 for waves 4-7 at phase entry (reset at phase exit), on top of the k-step-outer PV loop
# speedup vs baseline: 1.0038x; 1.0038x over previous
.LBB0_1418:
	s_cmp_lt_i32 s4, 9
	s_cselect_b64 s[4:5], -1, 0
	s_and_b64 s[0:1], s[4:5], s[0:1]
	v_writelane_b32 v236, s0, 11
	s_andn2_b64 vcc, exec, s[0:1]
	s_nop 0
	v_writelane_b32 v236, s1, 12
	s_cbranch_vccnz .LBB0_1581
	s_cmpk_gt_i32 s87, 0x1ff
	s_cbranch_scc1 .LBB0_1581
	s_add_u32 s16, s72, 0x9800000
	s_addc_u32 s20, s73, 0
	s_add_u32 s18, s72, 0x5800000
	s_addc_u32 s83, s73, 0
	s_add_u32 s33, s72, 0xf800000
	s_addc_u32 s24, s73, 0
	s_add_u32 s26, s72, 0xd800000
	v_writelane_b32 v236, s97, 13
	s_addc_u32 s4, s73, 0
	v_writelane_b32 v236, s96, 14
	s_add_u32 s94, s72, 0x100000
	v_mov_b32_e32 v163, 0
	v_mbcnt_lo_u32_b32 v18, -1, 0
	v_writelane_b32 v236, s92, 15
	s_addc_u32 s95, s73, 0
	s_movk_i32 s27, 0xc00
	s_mov_b32 s19, 0x2aaaaaab
	s_movk_i32 s17, 0xff
	v_mov_b32_e32 v1, 0x20000
	v_mov_b32_e32 v183, 0x1000
	v_mov_b32_e32 v2, v163
	s_waitcnt lgkmcnt(0)
	v_mov_b32_e32 v3, v163
	v_mov_b32_e32 v4, v163
	v_mov_b32_e32 v5, v163
	v_mov_b32_e32 v6, v163
	v_mov_b32_e32 v7, v163
	v_mov_b32_e32 v8, v163
	v_mov_b32_e32 v9, v163
	v_mov_b32_e32 v10, v163
	v_mov_b32_e32 v11, v163
	v_mov_b32_e32 v12, v163
	v_mov_b32_e32 v13, v163
	v_mov_b32_e32 v14, v163
	v_mov_b32_e32 v15, v163
	v_mov_b32_e32 v16, v163
	v_mov_b32_e32 v17, v163
	s_mov_b64 s[30:31], 0x80000
	s_mov_b32 s88, 0x41000000
	s_mov_b64 s[76:77], 0x40000
	v_mbcnt_hi_u32_b32 v184, -1, v18
	v_mov_b32_e32 v185, 0xff800000
	v_writelane_b32 v236, s93, 16
	v_readfirstlane_b32 s0, v182
	s_lshr_b32 s0, s0, 8
	s_cmp_lg_u32 s0, 0
	s_cbranch_scc0 .Lmla_prio_skip
	s_setprio 1
.Lmla_prio_skip:
	s_branch .LBB0_1422
.LBB0_1421:
	s_or_b64 exec, exec, s[6:7]
	v_readlane_b32 s0, v236, 15
	s_add_i32 s87, s87, s0
	s_cmpk_lt_i32 s87, 0x200
	s_waitcnt lgkmcnt(0)
	s_barrier
	v_readlane_b32 s1, v236, 16
	s_cbranch_scc0 .LBB0_1580

.LBB0_1580:
	s_setprio 0
	v_readlane_b32 s92, v236, 15
	v_readlane_b32 s93, v236, 16
	v_readlane_b32 s96, v236, 14
	v_readlane_b32 s97, v236, 13
